# v21 + online softmax (DIFF, FOX): the running reference moves only when a row's new max exceeds it by > 8 log2 units (exact reformulation, P <= 2^8, f32 sums), so the O-rescale path (32-64 packed mult
# baseline (speedup 1.0000x reference)
.LBB0_324:
	v_cvt_f32_i32_e32 v199, v158
	s_and_b32 s21, s20, 0x4000
	v_add_u32_e32 v149, s21, v231
	v_add_u32_e32 v151, v149, v154
	ds_read_b128 v[160:163], v151 offset:32768
	ds_read_b128 v[164:167], v151 offset:40960
	ds_read_b128 v[168:171], v147
	v_fma_f32 v199, v198, v199, -v146
	v_mov_b32_e32 v68, v199
	v_fmamk_f32 v69, v198, 0xbf800000, v199
	v_fmamk_f32 v70, v198, 0xc0000000, v199
	v_fmamk_f32 v71, v198, 0xc0400000, v199
	v_fmamk_f32 v72, v198, 0xc1000000, v199
	v_fmamk_f32 v73, v198, 0xc1100000, v199
	v_fmamk_f32 v74, v198, 0xc1200000, v199
	v_fmamk_f32 v75, v198, 0xc1300000, v199
	v_fmamk_f32 v76, v198, 0xc1800000, v199
	v_fmamk_f32 v77, v198, 0xc1880000, v199
	v_fmamk_f32 v78, v198, 0xc1900000, v199
	v_fmamk_f32 v79, v198, 0xc1980000, v199
	v_fmamk_f32 v80, v198, 0xc1c00000, v199
	v_fmamk_f32 v81, v198, 0xc1c80000, v199
	v_fmamk_f32 v82, v198, 0xc1d00000, v199
	v_fmamk_f32 v83, v198, 0xc1d80000, v199
	v_fmamk_f32 v116, v198, 0xc2000000, v199
	v_fmamk_f32 v117, v198, 0xc2040000, v199
	v_fmamk_f32 v118, v198, 0xc2080000, v199
	v_fmamk_f32 v119, v198, 0xc20c0000, v199
	v_fmamk_f32 v120, v198, 0xc2200000, v199
	v_fmamk_f32 v121, v198, 0xc2240000, v199
	v_fmamk_f32 v122, v198, 0xc2280000, v199
	v_fmamk_f32 v123, v198, 0xc22c0000, v199
	v_fmamk_f32 v124, v198, 0xc2400000, v199
	v_fmamk_f32 v125, v198, 0xc2440000, v199
	v_fmamk_f32 v126, v198, 0xc2480000, v199
	v_fmamk_f32 v127, v198, 0xc24c0000, v199
	v_fmamk_f32 v128, v198, 0xc2600000, v199
	v_fmamk_f32 v129, v198, 0xc2640000, v199
	v_fmamk_f32 v130, v198, 0xc2680000, v199
	v_fmamk_f32 v131, v198, 0xc26c0000, v199
	v_add_u32_e32 v151, v149, v155
	s_waitcnt lgkmcnt(0)
	v_mfma_f32_32x32x16_bf16 v[68:83], v[160:163], v[168:171], v[68:83]
	v_mfma_f32_32x32x16_bf16 v[116:131], v[164:167], v[168:171], v[116:131]
	ds_read_b128 v[160:163], v151 offset:32768
	ds_read_b128 v[164:167], v151 offset:40960
	ds_read_b128 v[168:171], v147 offset:1024
	v_add_u32_e32 v151, v149, v156
	v_add_u32_e32 v149, v149, v157
	s_waitcnt lgkmcnt(0)
	v_mfma_f32_32x32x16_bf16 v[68:83], v[160:163], v[168:171], v[68:83]
	v_mfma_f32_32x32x16_bf16 v[116:131], v[164:167], v[168:171], v[116:131]
	ds_read_b128 v[160:163], v151 offset:32768
	ds_read_b128 v[164:167], v151 offset:40960
	ds_read_b128 v[168:171], v147 offset:2048
	s_waitcnt lgkmcnt(0)
	v_mfma_f32_32x32x16_bf16 v[68:83], v[160:163], v[168:171], v[68:83]
	v_mfma_f32_32x32x16_bf16 v[116:131], v[164:167], v[168:171], v[116:131]
	ds_read_b128 v[160:163], v149 offset:32768
	ds_read_b128 v[164:167], v149 offset:40960
	ds_read_b128 v[168:171], v147 offset:3072
	s_waitcnt lgkmcnt(0)
	v_mfma_f32_32x32x16_bf16 v[68:83], v[160:163], v[168:171], v[68:83]
	v_mfma_f32_32x32x16_bf16 v[116:131], v[164:167], v[168:171], v[116:131]
	s_nop 10
	v_max_f32_e32 v149, v69, v69
	v_max_f32_e32 v151, v68, v68
	v_max_f32_e32 v149, v151, v149
	v_max3_f32 v149, v149, v70, v71
	v_max3_f32 v149, v149, v72, v73
	v_max3_f32 v149, v149, v74, v75
	v_max3_f32 v149, v149, v76, v77
	v_max3_f32 v149, v149, v78, v79
	v_max3_f32 v149, v149, v80, v81
	v_max3_f32 v149, v149, v82, v83
	v_max3_f32 v149, v149, v116, v117
	v_max3_f32 v149, v149, v118, v119
	v_max3_f32 v149, v149, v120, v121
	v_max3_f32 v149, v149, v122, v123
	v_max3_f32 v149, v149, v124, v125
	v_max3_f32 v149, v149, v126, v127
	v_max3_f32 v149, v149, v128, v129
	v_max3_f32 v149, v149, v130, v131
	v_mov_b32_e32 v151, v149
	s_nop 1
	v_permlane32_swap_b32_e32 v149, v151
	v_max3_f32 v152, v149, v151, 0
	v_cmp_lt_f32_e32 vcc, 0x41000000, v152
	s_nop 1
	v_cndmask_b32_e32 v152, 0, v152, vcc
	v_exp_f32_e64 v149, -v152
	v_cmp_neq_f32_e32 vcc, 0, v152
	s_cbranch_vccz .LBB0_328
	s_and_saveexec_b64 s[22:23], s[40:41]
	ds_write_b32 v232, v149
	s_or_b64 exec, exec, s[22:23]
	s_waitcnt lgkmcnt(0)
	v_add_u32_e32 v151, s33, v229
	ds_read_b128 v[160:163], v151 offset:64
	ds_read_b128 v[164:167], v151 offset:96
	ds_read_b128 v[168:171], v151
	ds_read_b128 v[172:175], v151 offset:32
	v_pk_add_f32 v[68:69], v[68:69], v[152:153] op_sel_hi:[1,0] neg_lo:[0,1] neg_hi:[0,1]
	v_pk_add_f32 v[116:117], v[116:117], v[152:153] op_sel_hi:[1,0] neg_lo:[0,1] neg_hi:[0,1]
	v_pk_add_f32 v[70:71], v[70:71], v[152:153] op_sel_hi:[1,0] neg_lo:[0,1] neg_hi:[0,1]
	v_pk_add_f32 v[118:119], v[118:119], v[152:153] op_sel_hi:[1,0] neg_lo:[0,1] neg_hi:[0,1]
	v_pk_add_f32 v[72:73], v[72:73], v[152:153] op_sel_hi:[1,0] neg_lo:[0,1] neg_hi:[0,1]
	v_pk_add_f32 v[120:121], v[120:121], v[152:153] op_sel_hi:[1,0] neg_lo:[0,1] neg_hi:[0,1]
	v_pk_add_f32 v[74:75], v[74:75], v[152:153] op_sel_hi:[1,0] neg_lo:[0,1] neg_hi:[0,1]
	v_pk_add_f32 v[122:123], v[122:123], v[152:153] op_sel_hi:[1,0] neg_lo:[0,1] neg_hi:[0,1]
	v_pk_add_f32 v[76:77], v[76:77], v[152:153] op_sel_hi:[1,0] neg_lo:[0,1] neg_hi:[0,1]
	v_pk_add_f32 v[124:125], v[124:125], v[152:153] op_sel_hi:[1,0] neg_lo:[0,1] neg_hi:[0,1]
	v_pk_add_f32 v[78:79], v[78:79], v[152:153] op_sel_hi:[1,0] neg_lo:[0,1] neg_hi:[0,1]
	v_pk_add_f32 v[126:127], v[126:127], v[152:153] op_sel_hi:[1,0] neg_lo:[0,1] neg_hi:[0,1]
	v_pk_add_f32 v[80:81], v[80:81], v[152:153] op_sel_hi:[1,0] neg_lo:[0,1] neg_hi:[0,1]
	v_pk_add_f32 v[128:129], v[128:129], v[152:153] op_sel_hi:[1,0] neg_lo:[0,1] neg_hi:[0,1]
	v_pk_add_f32 v[82:83], v[82:83], v[152:153] op_sel_hi:[1,0] neg_lo:[0,1] neg_hi:[0,1]
	v_pk_add_f32 v[130:131], v[130:131], v[152:153] op_sel_hi:[1,0] neg_lo:[0,1] neg_hi:[0,1]
	s_waitcnt lgkmcnt(2)
	v_pk_mul_f32 v[64:65], v[64:65], v[164:165]
	v_pk_mul_f32 v[60:61], v[60:61], v[160:161]
	s_waitcnt lgkmcnt(0)
	v_pk_mul_f32 v[56:57], v[56:57], v[172:173]
	v_pk_mul_f32 v[66:67], v[66:67], v[166:167]
	v_pk_mul_f32 v[62:63], v[62:63], v[162:163]
	v_pk_mul_f32 v[58:59], v[58:59], v[174:175]
	v_pk_mul_f32 v[54:55], v[54:55], v[170:171]
	v_pk_mul_f32 v[52:53], v[52:53], v[168:169]
	v_pk_mul_f32 v[96:97], v[96:97], v[164:165]
	v_pk_mul_f32 v[92:93], v[92:93], v[160:161]
	v_pk_mul_f32 v[88:89], v[88:89], v[172:173]
	v_pk_mul_f32 v[98:99], v[98:99], v[166:167]
	v_pk_mul_f32 v[94:95], v[94:95], v[162:163]
	v_pk_mul_f32 v[90:91], v[90:91], v[174:175]
	v_pk_mul_f32 v[86:87], v[86:87], v[170:171]
	v_pk_mul_f32 v[84:85], v[84:85], v[168:169]
	v_pk_mul_f32 v[112:113], v[112:113], v[164:165]
	v_pk_mul_f32 v[108:109], v[108:109], v[160:161]
	v_pk_mul_f32 v[104:105], v[104:105], v[172:173]
	v_pk_mul_f32 v[114:115], v[114:115], v[166:167]
	v_pk_mul_f32 v[110:111], v[110:111], v[162:163]
	v_pk_mul_f32 v[106:107], v[106:107], v[174:175]
	v_pk_mul_f32 v[102:103], v[102:103], v[170:171]
	v_pk_mul_f32 v[100:101], v[100:101], v[168:169]
	v_pk_mul_f32 v[48:49], v[48:49], v[164:165]
	v_pk_mul_f32 v[44:45], v[44:45], v[160:161]
	v_pk_mul_f32 v[40:41], v[40:41], v[172:173]
	v_pk_mul_f32 v[50:51], v[50:51], v[166:167]
	v_pk_mul_f32 v[46:47], v[46:47], v[162:163]
	v_pk_mul_f32 v[42:43], v[42:43], v[174:175]
	v_pk_mul_f32 v[38:39], v[38:39], v[170:171]
	v_pk_mul_f32 v[36:37], v[36:37], v[168:169]

.LBB0_492:
	s_nop 8
	v_max_f32_e32 v164, v85, v85
	v_max_f32_e32 v180, v84, v84
	v_max_f32_e32 v164, v180, v164
	v_max3_f32 v164, v164, v86, v87
	v_max3_f32 v164, v164, v88, v89
	v_max3_f32 v164, v164, v90, v91
	v_max3_f32 v164, v164, v92, v93
	v_max3_f32 v164, v164, v94, v95
	v_max3_f32 v164, v164, v96, v97
	v_max3_f32 v164, v164, v98, v99
	v_max3_f32 v164, v164, v68, v69
	v_max3_f32 v164, v164, v70, v71
	v_max3_f32 v164, v164, v72, v73
	v_max3_f32 v164, v164, v74, v75
	v_max3_f32 v164, v164, v76, v77
	v_max3_f32 v164, v164, v78, v79
	v_max3_f32 v164, v164, v80, v81
	v_max3_f32 v164, v164, v82, v83
	v_mov_b32_e32 v180, v164
	s_nop 1
	v_permlane32_swap_b32_e32 v164, v180
	v_max_f32_e32 v180, v180, v180
	v_max_f32_e32 v164, v164, v164
	s_cmp_eq_u32 s31, 31
	v_max_f32_e32 v164, v164, v180
	v_max_f32_e32 v180, 0, v164
	v_cmp_lt_f32_e32 vcc, 0x41000000, v180
	s_nop 1
	v_cndmask_b32_e32 v180, 0, v180, vcc
	s_cselect_b64 vcc, -1, 0
	v_cndmask_b32_e32 v164, v180, v164, vcc
	v_exp_f32_e64 v180, -v164
	s_nop 0
	v_cndmask_b32_e64 v197, v180, 1.0, vcc
	v_cmp_neq_f32_e32 vcc, 0, v164
	s_cbranch_vccz .LBB0_496
	s_and_saveexec_b64 s[4:5], s[40:41]
	ds_write_b32 v184, v197
	s_or_b64 exec, exec, s[4:5]
	s_waitcnt lgkmcnt(0)
	v_add_u32_e32 v180, s35, v34
	ds_read_b128 v[198:201], v180 offset:64
	ds_read_b128 v[202:205], v180 offset:96
	ds_read_b128 v[206:209], v180
	ds_read_b128 v[210:213], v180 offset:32
	v_pk_add_f32 v[84:85], v[84:85], v[164:165] op_sel_hi:[1,0] neg_lo:[0,1] neg_hi:[0,1]
	v_pk_add_f32 v[68:69], v[68:69], v[164:165] op_sel_hi:[1,0] neg_lo:[0,1] neg_hi:[0,1]
	v_pk_add_f32 v[86:87], v[86:87], v[164:165] op_sel_hi:[1,0] neg_lo:[0,1] neg_hi:[0,1]
	v_pk_add_f32 v[70:71], v[70:71], v[164:165] op_sel_hi:[1,0] neg_lo:[0,1] neg_hi:[0,1]
	v_pk_add_f32 v[88:89], v[88:89], v[164:165] op_sel_hi:[1,0] neg_lo:[0,1] neg_hi:[0,1]
	v_pk_add_f32 v[72:73], v[72:73], v[164:165] op_sel_hi:[1,0] neg_lo:[0,1] neg_hi:[0,1]
	v_pk_add_f32 v[90:91], v[90:91], v[164:165] op_sel_hi:[1,0] neg_lo:[0,1] neg_hi:[0,1]
	v_pk_add_f32 v[74:75], v[74:75], v[164:165] op_sel_hi:[1,0] neg_lo:[0,1] neg_hi:[0,1]
	v_pk_add_f32 v[92:93], v[92:93], v[164:165] op_sel_hi:[1,0] neg_lo:[0,1] neg_hi:[0,1]
	v_pk_add_f32 v[76:77], v[76:77], v[164:165] op_sel_hi:[1,0] neg_lo:[0,1] neg_hi:[0,1]
	v_pk_add_f32 v[94:95], v[94:95], v[164:165] op_sel_hi:[1,0] neg_lo:[0,1] neg_hi:[0,1]
	v_pk_add_f32 v[78:79], v[78:79], v[164:165] op_sel_hi:[1,0] neg_lo:[0,1] neg_hi:[0,1]
	v_pk_add_f32 v[96:97], v[96:97], v[164:165] op_sel_hi:[1,0] neg_lo:[0,1] neg_hi:[0,1]
	v_pk_add_f32 v[80:81], v[80:81], v[164:165] op_sel_hi:[1,0] neg_lo:[0,1] neg_hi:[0,1]
	v_pk_add_f32 v[98:99], v[98:99], v[164:165] op_sel_hi:[1,0] neg_lo:[0,1] neg_hi:[0,1]
	v_pk_add_f32 v[82:83], v[82:83], v[164:165] op_sel_hi:[1,0] neg_lo:[0,1] neg_hi:[0,1]
	s_waitcnt lgkmcnt(2)
	v_pk_mul_f32 v[64:65], v[64:65], v[202:203]
	v_pk_mul_f32 v[60:61], v[60:61], v[198:199]
	s_waitcnt lgkmcnt(0)
	v_pk_mul_f32 v[56:57], v[56:57], v[210:211]
	v_pk_mul_f32 v[66:67], v[66:67], v[204:205]
	v_pk_mul_f32 v[62:63], v[62:63], v[200:201]
	v_pk_mul_f32 v[58:59], v[58:59], v[212:213]
	v_pk_mul_f32 v[54:55], v[54:55], v[208:209]
	v_pk_mul_f32 v[52:53], v[52:53], v[206:207]
	v_pk_mul_f32 v[48:49], v[48:49], v[202:203]
	v_pk_mul_f32 v[44:45], v[44:45], v[198:199]
	v_pk_mul_f32 v[40:41], v[40:41], v[210:211]
	v_pk_mul_f32 v[50:51], v[50:51], v[204:205]
	v_pk_mul_f32 v[46:47], v[46:47], v[200:201]
	v_pk_mul_f32 v[42:43], v[42:43], v[212:213]
	v_pk_mul_f32 v[38:39], v[38:39], v[208:209]
	v_pk_mul_f32 v[36:37], v[36:37], v[206:207]
	v_pk_mul_f32 v[30:31], v[30:31], v[202:203]
	v_pk_mul_f32 v[26:27], v[26:27], v[198:199]
	v_pk_mul_f32 v[22:23], v[22:23], v[210:211]
	v_pk_mul_f32 v[32:33], v[32:33], v[204:205]
	v_pk_mul_f32 v[28:29], v[28:29], v[200:201]
	v_pk_mul_f32 v[24:25], v[24:25], v[212:213]
	v_pk_mul_f32 v[20:21], v[20:21], v[208:209]
	v_pk_mul_f32 v[18:19], v[18:19], v[206:207]
	v_pk_mul_f32 v[14:15], v[14:15], v[202:203]
	v_pk_mul_f32 v[10:11], v[10:11], v[198:199]
	v_pk_mul_f32 v[6:7], v[6:7], v[210:211]
	v_pk_mul_f32 v[16:17], v[16:17], v[204:205]
	v_pk_mul_f32 v[12:13], v[12:13], v[200:201]
	v_pk_mul_f32 v[8:9], v[8:9], v[212:213]
	v_pk_mul_f32 v[4:5], v[4:5], v[208:209]
	v_pk_mul_f32 v[2:3], v[2:3], v[206:207]

.LBB0_507:
	s_nop 8
	v_max_f32_e32 v164, v85, v85
	v_max_f32_e32 v180, v84, v84
	v_max_f32_e32 v164, v180, v164
	v_max3_f32 v164, v164, v86, v87
	v_max3_f32 v164, v164, v88, v89
	v_max3_f32 v164, v164, v90, v91
	v_max3_f32 v164, v164, v92, v93
	v_max3_f32 v164, v164, v94, v95
	v_max3_f32 v164, v164, v96, v97
	v_max3_f32 v164, v164, v98, v99
	v_max3_f32 v164, v164, v68, v69
	v_max3_f32 v164, v164, v70, v71
	v_max3_f32 v164, v164, v72, v73
	v_max3_f32 v164, v164, v74, v75
	v_max3_f32 v164, v164, v76, v77
	v_max3_f32 v164, v164, v78, v79
	v_max3_f32 v164, v164, v80, v81
	v_max3_f32 v164, v164, v82, v83
	v_mov_b32_e32 v180, v164
	s_nop 1
	v_permlane32_swap_b32_e32 v164, v180
	v_max_f32_e32 v180, v180, v180
	v_max_f32_e32 v164, v164, v164
	s_cmp_eq_u32 s31, 30
	v_max_f32_e32 v164, v164, v180
	v_max_f32_e32 v180, 0, v164
	v_cmp_lt_f32_e32 vcc, 0x41000000, v180
	s_nop 1
	v_cndmask_b32_e32 v180, 0, v180, vcc
	s_cselect_b64 vcc, -1, 0
	v_cndmask_b32_e32 v164, v180, v164, vcc
	v_exp_f32_e64 v180, -v164
	s_nop 0
	v_cndmask_b32_e64 v197, v180, 1.0, vcc
	v_cmp_neq_f32_e32 vcc, 0, v164
	s_cbranch_vccz .LBB0_511
	s_and_saveexec_b64 s[4:5], s[40:41]
	ds_write_b32 v184, v197
	s_or_b64 exec, exec, s[4:5]
	s_waitcnt lgkmcnt(0)
	v_add_u32_e32 v180, s35, v34
	ds_read_b128 v[198:201], v180 offset:64
	ds_read_b128 v[202:205], v180 offset:96
	ds_read_b128 v[206:209], v180
	ds_read_b128 v[210:213], v180 offset:32
	v_pk_add_f32 v[84:85], v[84:85], v[164:165] op_sel_hi:[1,0] neg_lo:[0,1] neg_hi:[0,1]
	v_pk_add_f32 v[68:69], v[68:69], v[164:165] op_sel_hi:[1,0] neg_lo:[0,1] neg_hi:[0,1]
	v_pk_add_f32 v[86:87], v[86:87], v[164:165] op_sel_hi:[1,0] neg_lo:[0,1] neg_hi:[0,1]
	v_pk_add_f32 v[70:71], v[70:71], v[164:165] op_sel_hi:[1,0] neg_lo:[0,1] neg_hi:[0,1]
	v_pk_add_f32 v[88:89], v[88:89], v[164:165] op_sel_hi:[1,0] neg_lo:[0,1] neg_hi:[0,1]
	v_pk_add_f32 v[72:73], v[72:73], v[164:165] op_sel_hi:[1,0] neg_lo:[0,1] neg_hi:[0,1]
	v_pk_add_f32 v[90:91], v[90:91], v[164:165] op_sel_hi:[1,0] neg_lo:[0,1] neg_hi:[0,1]
	v_pk_add_f32 v[74:75], v[74:75], v[164:165] op_sel_hi:[1,0] neg_lo:[0,1] neg_hi:[0,1]
	v_pk_add_f32 v[92:93], v[92:93], v[164:165] op_sel_hi:[1,0] neg_lo:[0,1] neg_hi:[0,1]
	v_pk_add_f32 v[76:77], v[76:77], v[164:165] op_sel_hi:[1,0] neg_lo:[0,1] neg_hi:[0,1]
	v_pk_add_f32 v[94:95], v[94:95], v[164:165] op_sel_hi:[1,0] neg_lo:[0,1] neg_hi:[0,1]
	v_pk_add_f32 v[78:79], v[78:79], v[164:165] op_sel_hi:[1,0] neg_lo:[0,1] neg_hi:[0,1]
	v_pk_add_f32 v[96:97], v[96:97], v[164:165] op_sel_hi:[1,0] neg_lo:[0,1] neg_hi:[0,1]
	v_pk_add_f32 v[80:81], v[80:81], v[164:165] op_sel_hi:[1,0] neg_lo:[0,1] neg_hi:[0,1]
	v_pk_add_f32 v[98:99], v[98:99], v[164:165] op_sel_hi:[1,0] neg_lo:[0,1] neg_hi:[0,1]
	v_pk_add_f32 v[82:83], v[82:83], v[164:165] op_sel_hi:[1,0] neg_lo:[0,1] neg_hi:[0,1]
	s_waitcnt lgkmcnt(2)
	v_pk_mul_f32 v[64:65], v[64:65], v[202:203]
	v_pk_mul_f32 v[60:61], v[60:61], v[198:199]
	s_waitcnt lgkmcnt(0)
	v_pk_mul_f32 v[56:57], v[56:57], v[210:211]
	v_pk_mul_f32 v[66:67], v[66:67], v[204:205]
	v_pk_mul_f32 v[62:63], v[62:63], v[200:201]
	v_pk_mul_f32 v[58:59], v[58:59], v[212:213]
	v_pk_mul_f32 v[54:55], v[54:55], v[208:209]
	v_pk_mul_f32 v[52:53], v[52:53], v[206:207]
	v_pk_mul_f32 v[48:49], v[48:49], v[202:203]
	v_pk_mul_f32 v[44:45], v[44:45], v[198:199]
	v_pk_mul_f32 v[40:41], v[40:41], v[210:211]
	v_pk_mul_f32 v[50:51], v[50:51], v[204:205]
	v_pk_mul_f32 v[46:47], v[46:47], v[200:201]
	v_pk_mul_f32 v[42:43], v[42:43], v[212:213]
	v_pk_mul_f32 v[38:39], v[38:39], v[208:209]
	v_pk_mul_f32 v[36:37], v[36:37], v[206:207]
	v_pk_mul_f32 v[30:31], v[30:31], v[202:203]
	v_pk_mul_f32 v[26:27], v[26:27], v[198:199]
	v_pk_mul_f32 v[22:23], v[22:23], v[210:211]
	v_pk_mul_f32 v[32:33], v[32:33], v[204:205]
	v_pk_mul_f32 v[28:29], v[28:29], v[200:201]
	v_pk_mul_f32 v[24:25], v[24:25], v[212:213]
	v_pk_mul_f32 v[20:21], v[20:21], v[208:209]
	v_pk_mul_f32 v[18:19], v[18:19], v[206:207]
	v_pk_mul_f32 v[14:15], v[14:15], v[202:203]
	v_pk_mul_f32 v[10:11], v[10:11], v[198:199]
	v_pk_mul_f32 v[6:7], v[6:7], v[210:211]
	v_pk_mul_f32 v[16:17], v[16:17], v[204:205]
	v_pk_mul_f32 v[12:13], v[12:13], v[200:201]
	v_pk_mul_f32 v[8:9], v[8:9], v[212:213]
	v_pk_mul_f32 v[4:5], v[4:5], v[208:209]
	v_pk_mul_f32 v[2:3], v[2:3], v[206:207]
